# v127 + prologue context-stream copy de-serialised (4 loads, one wait, 4 stores)
# baseline (speedup 1.0000x reference)
.LBB0_604:
	v_ashrrev_i32_e32 v5, 31, v4
	v_lshlrev_b64 v[10:11], 4, v[4:5]
	s_lshl_b32 s10, s5, 4
	s_mov_b32 s11, 0
	v_lshl_add_u64 v[6:7], s[76:77], 0, v[10:11]
	global_load_dwordx4 v[12:15], v[6:7], off
	v_lshl_add_u64 v[6:7], v[6:7], 0, s[10:11]
	global_load_dwordx4 v[20:23], v[6:7], off
	v_lshl_add_u64 v[6:7], v[6:7], 0, s[10:11]
	global_load_dwordx4 v[28:31], v[6:7], off
	v_lshl_add_u64 v[6:7], v[6:7], 0, s[10:11]
	global_load_dwordx4 v[32:35], v[6:7], off
	v_lshl_add_u64 v[10:11], s[54:55], 0, v[10:11]
	s_waitcnt vmcnt(0)
	global_store_dwordx4 v[10:11], v[12:15], off
	v_lshl_add_u64 v[10:11], v[10:11], 0, s[10:11]
	global_store_dwordx4 v[10:11], v[20:23], off
	v_lshl_add_u64 v[10:11], v[10:11], 0, s[10:11]
	global_store_dwordx4 v[10:11], v[28:31], off
	v_lshl_add_u64 v[10:11], v[10:11], 0, s[10:11]
	global_store_dwordx4 v[10:11], v[32:35], off
